# attention ping-pong (4 barriers/tile, waves 4-7 skewed), hand-written lean LDS-DMA issue in softmax slot, softmax VALU trim, K-fragment reads interleaved with PV MFMAs; P10 batched epilogue
# speedup vs baseline: 1.0191x; 1.0121x over previous
.LBB0_1264:
	s_lshl_b32 s87, s35, 2
	s_xor_b64 s[16:17], s[44:45], -1
	s_add_i32 s87, s87, 4
	s_ashr_i32 s89, s86, 6
	s_movk_i32 s35, 0x110
	s_cmp_lt_u32 s85, 26
	v_mad_u32_u24 v229, v227, s35, v214
	s_cselect_b64 s[50:51], -1, 0
	s_lshl_b32 s35, s85, 10
	s_cmp_lt_u32 s6, 26
	s_cselect_b64 s[54:55], -1, 0
	s_lshl_b32 s44, s6, 10
	s_cmp_lt_u32 s7, 26
	s_cselect_b64 s[58:59], -1, 0
	s_lshl_b32 s45, s7, 10
	s_cmp_lt_u32 s14, 26
	s_cselect_b64 s[6:7], -1, 0
	s_lshl_b32 s46, s14, 10
	s_cmp_lt_u32 s15, 26
	s_cselect_b64 s[66:67], -1, 0
	s_lshl_b32 s47, s15, 10
	s_cmp_lt_u32 s33, 26
	s_cselect_b64 s[14:15], -1, 0
	s_lshl_b32 s33, s33, 10
	s_add_i32 s88, s35, 0
	s_add_i32 s90, s44, 0
	s_add_i32 s91, s45, 0
	s_add_i32 s92, s46, 0
	s_add_i32 s93, s47, 0
	s_add_i32 s94, s33, 0
	s_and_b64 s[44:45], s[50:51], exec
	s_cselect_b32 s33, s73, s37
	s_cselect_b32 s35, s74, s38
	s_cmp_lt_i32 s85, 26
	s_cselect_b64 s[44:45], -1, 0
	s_and_b64 s[46:47], s[48:49], exec
	s_cselect_b32 s47, s9, s35
	s_cselect_b32 s46, s8, s33
	s_and_b64 s[50:51], s[50:51], exec
	s_cselect_b32 s33, 13, 7
	s_and_b64 s[48:49], s[48:49], exec
	s_cselect_b32 s95, 18, s33
	s_and_b64 s[48:49], s[54:55], exec
	s_cselect_b32 s33, s73, s37
	s_cselect_b32 s35, s74, s38
	s_cmp_lt_i32 s85, 18
	s_cselect_b64 s[48:49], -1, 0
	s_and_b64 s[50:51], exec, s[52:53]
	s_cselect_b32 s51, s9, s35
	s_cselect_b32 s50, s8, s33
	s_and_b64 s[54:55], s[54:55], exec
	s_cselect_b32 s33, 13, 7
	s_and_b64 s[52:53], exec, s[52:53]
	s_cselect_b32 s96, 18, s33
	s_and_b64 s[52:53], s[58:59], exec
	s_cselect_b32 s33, s73, s37
	s_cselect_b32 s35, s74, s38
	s_cmp_lt_i32 s85, 10
	s_cselect_b64 s[52:53], -1, 0
	s_and_b64 s[54:55], exec, s[56:57]
	s_cselect_b32 s55, s9, s35
	s_cselect_b32 s54, s8, s33
	s_and_b64 s[58:59], s[58:59], exec
	s_cselect_b32 s33, 13, 7
	s_and_b64 s[56:57], exec, s[56:57]
	s_cselect_b32 s97, 18, s33
	s_and_b64 s[56:57], s[6:7], exec
	s_cselect_b32 s33, s73, s37
	s_cselect_b32 s35, s74, s38
	s_cmp_lt_i32 s85, 2
	s_cselect_b64 s[56:57], -1, 0
	s_and_b64 s[58:59], exec, s[60:61]
	s_cselect_b32 s59, s9, s35
	s_cselect_b32 s58, s8, s33
	s_and_b64 s[6:7], s[6:7], exec
	v_add_u32_e32 v230, 0, v229
	s_cselect_b32 s33, 13, 7
	s_and_b64 s[6:7], exec, s[60:61]
	s_waitcnt vmcnt(0)
	s_waitcnt vmcnt(0) lgkmcnt(0)
	s_barrier
	ds_read_b128 v[112:115], v1
	ds_read_b128 v[116:119], v1 offset:32
	ds_read_b128 v[120:123], v1 offset:64
	ds_read_b128 v[124:127], v1 offset:96
	ds_read_b128 v[168:171], v230
	ds_read_b128 v[160:163], v230 offset:32
	ds_read_b128 v[164:167], v230 offset:64
	ds_read_b128 v[152:155], v230 offset:96
	ds_read_b128 v[156:159], v230 offset:128
	ds_read_b128 v[128:131], v230 offset:160
	ds_read_b128 v[132:135], v230 offset:192
	ds_read_b128 v[136:139], v230 offset:224
	s_cselect_b32 s6, 18, s33
	s_and_b64 s[60:61], s[66:67], exec
	v_lshlrev_b32_e32 v1, 7, v227
	s_cselect_b32 s7, s73, s37
	s_cselect_b32 s33, s74, s38
	s_cmp_lt_i32 s85, -6
	v_sub_u32_e32 v1, v229, v1
	s_cselect_b64 s[60:61], -1, 0
	s_and_b64 s[62:63], exec, s[64:65]
	v_add_u32_e32 v231, 0, v1
	s_cselect_b32 s63, s9, s33
	s_cselect_b32 s62, s8, s7
	s_and_b64 s[66:67], s[66:67], exec
	ds_read_b128 v[140:143], v231 offset:17408
	ds_read_b128 v[144:147], v231 offset:17440
	ds_read_b128 v[148:151], v231 offset:17472
	ds_read_b128 v[208:211], v231 offset:17504
	s_cselect_b32 s7, 13, 7
	s_and_b64 s[64:65], exec, s[64:65]
	s_cselect_b32 s7, 18, s7
	s_and_b64 s[64:65], s[14:15], exec
	s_cselect_b32 s33, s73, s37
	s_cselect_b32 s35, s74, s38
	s_cmp_lt_i32 s85, -14
	s_cselect_b64 s[64:65], -1, 0
	s_and_b64 s[66:67], exec, s[68:69]
	v_mul_u32_u24_e32 v2, 0x90, v227
	s_cselect_b32 s67, s9, s35
	s_cselect_b32 s66, s8, s33
	s_and_b64 s[14:15], s[14:15], exec
	v_mov_b32_e32 v14, v215
	v_mov_b32_e32 v15, v215
	v_lshlrev_b32_e32 v232, 2, v0
	s_cselect_b32 s33, 13, 7
	s_and_b64 s[14:15], exec, s[68:69]
	v_add_u32_e32 v233, v2, v214
	v_mov_b32_e32 v0, v215
	v_mov_b32_e32 v1, v215
	v_mov_b32_e32 v2, v215
	v_mov_b32_e32 v3, v215
	v_mov_b32_e32 v4, v215
	v_mov_b32_e32 v5, v215
	v_mov_b32_e32 v6, v215
	v_mov_b32_e32 v7, v215
	v_mov_b32_e32 v8, v215
	v_mov_b32_e32 v9, v215
	v_mov_b32_e32 v10, v215
	v_mov_b32_e32 v11, v215
	v_mov_b32_e32 v12, v215
	v_mov_b32_e32 v13, v215
	v_mov_b64_e32 v[30:31], v[14:15]
	v_mov_b64_e32 v[46:47], v[14:15]
	v_mov_b64_e32 v[62:63], v[14:15]
	s_cselect_b32 s33, 18, s33
	v_add_u32_e32 v234, 0, v233
	s_add_i32 s14, s34, 0x100
	s_mov_b32 s15, 0
	v_mov_b32_e32 v235, 0
	v_mov_b32_e32 v236, 0xff800000
	v_mov_b32_e32 v252, 0xff800000
	v_mov_b64_e32 v[28:29], v[12:13]
	v_mov_b64_e32 v[26:27], v[10:11]
	v_mov_b64_e32 v[24:25], v[8:9]
	v_mov_b64_e32 v[22:23], v[6:7]
	v_mov_b64_e32 v[20:21], v[4:5]
	v_mov_b64_e32 v[18:19], v[2:3]
	v_mov_b64_e32 v[16:17], v[0:1]
	v_mov_b64_e32 v[44:45], v[12:13]
	v_mov_b64_e32 v[42:43], v[10:11]
	v_mov_b64_e32 v[40:41], v[8:9]
	v_mov_b64_e32 v[38:39], v[6:7]
	v_mov_b64_e32 v[36:37], v[4:5]
	v_mov_b64_e32 v[34:35], v[2:3]
	v_mov_b64_e32 v[32:33], v[0:1]
	v_mov_b64_e32 v[60:61], v[12:13]
	v_mov_b64_e32 v[58:59], v[10:11]
	v_mov_b64_e32 v[56:57], v[8:9]
	v_mov_b64_e32 v[54:55], v[6:7]
	v_mov_b64_e32 v[52:53], v[4:5]
	v_mov_b64_e32 v[50:51], v[2:3]
	v_mov_b64_e32 v[48:49], v[0:1]
	s_mov_b32 s35, 0
	s_and_b32 s45, s85, 3
	s_lshl_b32 s44, s45, 10
	s_mov_b32 s52, s73
	s_mov_b32 s53, s74
	s_mov_b32 s54, s37
	s_mov_b32 s55, s38
	s_cmp_ge_u32 s85, 4
	s_cbranch_scc1 .Lxd_sy
	s_add_i32 s18, s45, 0
	s_lshl_b32 s18, s18, 10
	v_lshl_add_u32 v72, v219, 4, s18
	s_mov_b32 s19, 15790321
	v_mul_hi_u32 v73, v72, s19
	v_mul_u32_u24_e32 v74, 272, v73
	v_sub_u32_e32 v74, v72, v74
	v_min_u32_e32 v74, 240, v74
	v_lshlrev_b32_e32 v75, 12, v73
	v_add3_u32 v221, v75, v74, s84
	s_add_i32 s18, s45, 4
	s_lshl_b32 s18, s18, 10
	v_lshl_add_u32 v72, v219, 4, s18
	s_mov_b32 s19, 15790321
	v_mul_hi_u32 v73, v72, s19
	v_mul_u32_u24_e32 v74, 272, v73
	v_sub_u32_e32 v74, v72, v74
	v_min_u32_e32 v74, 240, v74
	v_lshlrev_b32_e32 v75, 12, v73
	v_add3_u32 v222, v75, v74, s84
	s_add_i32 s18, s45, 8
	s_lshl_b32 s18, s18, 10
	v_lshl_add_u32 v72, v219, 4, s18
	s_mov_b32 s19, 15790321
	v_mul_hi_u32 v73, v72, s19
	v_mul_u32_u24_e32 v74, 272, v73
	v_sub_u32_e32 v74, v72, v74
	v_min_u32_e32 v74, 240, v74
	v_lshlrev_b32_e32 v75, 12, v73
	v_add3_u32 v223, v75, v74, s84
	s_add_i32 s18, s45, 12
	s_lshl_b32 s18, s18, 10
	v_lshl_add_u32 v72, v219, 4, s18
	s_mov_b32 s19, 15790321
	v_mul_hi_u32 v73, v72, s19
	v_mul_u32_u24_e32 v74, 272, v73
	v_sub_u32_e32 v74, v72, v74
	v_min_u32_e32 v74, 240, v74
	v_lshlrev_b32_e32 v75, 12, v73
	v_add3_u32 v224, v75, v74, s84
	s_cmp_ge_u32 s45, 1
	s_cselect_b32 s18, -1, 16
	s_mov_b32 s24, 29826162
	s_mov_b32 s25, 15790321
	s_cselect_b32 s19, s24, s25
	s_mov_b32 s24, 144
	s_mov_b32 s25, 272
	s_cselect_b32 s20, s24, s25
	s_mov_b32 s24, 112
	s_mov_b32 s25, 240
	s_cselect_b32 s21, s24, s25
	s_cselect_b32 s22, 7, 12
	s_cselect_b32 s23, 0, s84
	s_add_i32 s18, s45, s18
	s_lshl_b32 s18, s18, 10
	v_lshl_add_u32 v72, v219, 4, s18
	v_mul_hi_u32 v73, v72, s19
	v_mul_lo_u32 v74, v73, s20
	v_sub_u32_e32 v74, v72, v74
	v_min_u32_e32 v74, s21, v74
	v_lshlrev_b32_e32 v75, s22, v73
	v_add3_u32 v225, v75, v74, s23
	s_add_i32 s18, s45, 3
	s_lshl_b32 s18, s18, 10
	v_lshl_add_u32 v72, v219, 4, s18
	s_mov_b32 s19, 29826162
	v_mul_hi_u32 v73, v72, s19
	v_mul_u32_u24_e32 v74, 144, v73
	v_sub_u32_e32 v74, v72, v74
	v_min_u32_e32 v74, 112, v74
	v_lshlrev_b32_e32 v75, 7, v73
	v_add_u32_e32 v226, v75, v74
	s_cmp_ge_u32 s45, 1
	s_cselect_b32 s95, 13, 18
	s_cselect_b32 s46, s73, s8
	s_cselect_b32 s47, s74, s9
	s_branch .Lxd_sdone
.Lxd_sy:
	s_cmp_ge_u32 s45, 2
	s_cselect_b32 s18, -2, 7
	s_mov_b32 s24, 29826162
	s_mov_b32 s25, 29826162
	s_cselect_b32 s19, s24, s25
	s_mov_b32 s24, 144
	s_mov_b32 s25, 144
	s_cselect_b32 s20, s24, s25
	s_mov_b32 s24, 112
	s_mov_b32 s25, 112
	s_cselect_b32 s21, s24, s25
	s_cselect_b32 s22, 15, 7
	s_cselect_b32 s23, s83, 0
	s_add_i32 s18, s45, s18
	s_lshl_b32 s18, s18, 10
	v_lshl_add_u32 v72, v219, 4, s18
	v_mul_hi_u32 v73, v72, s19
	v_mul_lo_u32 v74, v73, s20
	v_sub_u32_e32 v74, v72, v74
	v_min_u32_e32 v74, s21, v74
	v_lshlrev_b32_e32 v75, s22, v73
	v_add3_u32 v221, v75, v74, s23
	s_add_i32 s18, s45, 2
	s_lshl_b32 s18, s18, 10
	v_lshl_add_u32 v72, v219, 4, s18
	s_mov_b32 s19, 29826162
	v_mul_hi_u32 v73, v72, s19
	v_mul_u32_u24_e32 v74, 144, v73
	v_sub_u32_e32 v74, v72, v74
	v_min_u32_e32 v74, 112, v74
	v_lshlrev_b32_e32 v75, 15, v73
	v_add3_u32 v222, v75, v74, s83
	s_add_i32 s18, s45, 6
	s_lshl_b32 s18, s18, 10
	v_lshl_add_u32 v72, v219, 4, s18
	s_mov_b32 s19, 29826162
	v_mul_hi_u32 v73, v72, s19
	v_mul_u32_u24_e32 v74, 144, v73
	v_sub_u32_e32 v74, v72, v74
	v_min_u32_e32 v74, 112, v74
	v_lshlrev_b32_e32 v75, 15, v73
	v_add3_u32 v223, v75, v74, s83
	s_add_i32 s18, s45, 10
	s_lshl_b32 s18, s18, 10
	v_lshl_add_u32 v72, v219, 4, s18
	s_mov_b32 s19, 29826162
	v_mul_hi_u32 v73, v72, s19
	v_mul_u32_u24_e32 v74, 144, v73
	v_sub_u32_e32 v74, v72, v74
	v_min_u32_e32 v74, 112, v74
	v_lshlrev_b32_e32 v75, 15, v73
	v_add3_u32 v224, v75, v74, s83
	s_add_i32 s18, s45, 14
	s_lshl_b32 s18, s18, 10
	v_lshl_add_u32 v72, v219, 4, s18
	s_mov_b32 s19, 29826162
	v_mul_hi_u32 v73, v72, s19
	v_mul_u32_u24_e32 v74, 144, v73
	v_sub_u32_e32 v74, v72, v74
	v_min_u32_e32 v74, 112, v74
	v_lshlrev_b32_e32 v75, 15, v73
	v_add3_u32 v225, v75, v74, s83
	s_cmp_ge_u32 s45, 2
	s_cselect_b32 s96, 7, 13
	s_cselect_b32 s50, s37, s73
	s_cselect_b32 s51, s38, s74
.Lxd_sdone:
	s_cmp_ge_u32 s85, 4
	s_cbranch_scc0 .Lpp_x
	s_barrier

.LBB0_1278:
	s_cmp_le_i32 s35, s89
	s_cselect_b64 s[70:71], -1, 0
	s_cmp_gt_i32 s35, s89
	s_cbranch_scc1 .LBB0_1288
	s_and_b32 vcc_lo, s35, 1
	s_mul_i32 vcc_hi, vcc_lo, 0x4800
	v_add_u32_e32 v237, vcc_hi, v234
	v_add_u32_e32 v238, 0xd000, v237
	s_mulk_i32 vcc_lo, 0x6800
	s_add_i32 vcc_lo, vcc_lo, 0
	s_setprio 1
	s_waitcnt lgkmcnt(0)
	v_mfma_f32_32x32x16_bf16 v[64:79], v[168:171], v[80:83], 0
	ds_read_b128 v[180:183], v237 offset:53248
	ds_read_b128 v[176:179], v237 offset:53280
	v_add_u32_e32 v172, vcc_lo, v229
	v_add_u32_e32 v239, vcc_lo, v233
	v_mfma_f32_32x32x16_bf16 v[64:79], v[160:163], v[84:87], v[64:79]
	ds_read_b128 v[196:199], v237 offset:57856
	ds_read_b128 v[188:191], v237 offset:62464
	v_mfma_f32_32x32x16_bf16 v[64:79], v[164:167], v[88:91], v[64:79]
	ds_read_b128 v[200:203], v238 offset:13824
	ds_read_b128 v[184:187], v238 offset:13856
	v_mfma_f32_32x32x16_bf16 v[64:79], v[152:155], v[92:95], v[64:79]
	ds_read_b128 v[204:207], v237 offset:57888
	ds_read_b128 v[192:195], v237 offset:62496
	v_mfma_f32_32x32x16_bf16 v[64:79], v[156:159], v[96:99], v[64:79]
	ds_read_b128 v[168:171], v172 offset:8704
	ds_read_b128 v[160:163], v172 offset:8736
	v_mfma_f32_32x32x16_bf16 v[64:79], v[128:131], v[100:103], v[64:79]
	ds_read_b128 v[164:167], v172 offset:8768
	ds_read_b128 v[152:155], v172 offset:8800
	v_mfma_f32_32x32x16_bf16 v[64:79], v[132:135], v[104:107], v[64:79]
	ds_read_b128 v[156:159], v172 offset:8832
	ds_read_b128 v[128:131], v172 offset:8864
	v_mfma_f32_32x32x16_bf16 v[64:79], v[136:139], v[108:111], v[64:79]
	ds_read_b128 v[132:135], v172 offset:8896
	ds_read_b128 v[136:139], v172 offset:8928
	v_mfma_f32_32x32x16_bf16 v[64:79], v[140:143], v[112:115], v[64:79]
	ds_read_b128 v[140:143], v239 offset:22016
	ds_read_b128 v[172:175], v239 offset:22112
	v_mfma_f32_32x32x16_bf16 v[64:79], v[144:147], v[116:119], v[64:79]
	ds_read_b128 v[144:147], v239 offset:22048
	v_mfma_f32_32x32x16_bf16 v[64:79], v[148:151], v[120:123], v[64:79]
	ds_read_b128 v[148:151], v239 offset:22080
	v_mfma_f32_32x32x16_bf16 v[64:79], v[208:211], v[124:127], v[64:79]
	s_setprio 0
	s_barrier
	s_and_b64 vcc, exec, s[68:69]
	s_cbranch_vccnz .Ldmq_end
	s_cmp_ge_u32 s85, 4
	s_cbranch_scc1 .Lxdq_y
	s_and_b32 s99, s34, 1
	s_mul_i32 s98, s99, 0x4800
	s_addk_i32 s98, 0x6800
	s_mulk_i32 s99, 0x6800
	s_add_i32 s99, s99, s44
	s_add_i32 s98, s98, s44
	s_lshl_b32 s94, s34, 18
	s_lshl_b32 s90, s34, 13
	s_lshl_b32 s91, s34, 7
	s_add_i32 m0, s99, 0x0
	v_add_u32_e32 v255, s94, v221
	global_load_lds_dwordx4 v255, s[8:9]
	s_add_i32 m0, s99, 0x1000
	v_add_u32_e32 v255, s94, v222
	global_load_lds_dwordx4 v255, s[8:9]
	s_add_i32 m0, s99, 0x2000
	v_add_u32_e32 v255, s94, v223
	global_load_lds_dwordx4 v255, s[8:9]
	s_add_i32 m0, s99, 0x3000
	v_add_u32_e32 v255, s94, v224
	global_load_lds_dwordx4 v255, s[8:9]
	s_lshl_b32 s92, s34, s95
	s_add_i32 m0, s99, 0x4000
	v_add_u32_e32 v255, s92, v225
	global_load_lds_dwordx4 v255, s[46:47]
	s_add_i32 m0, s99, 0x5000
	v_add_u32_e32 v255, s90, v226
	global_load_lds_dwordx4 v255, s[52:53]
	s_branch .Ldmq_end
.Lxdq_y:
	s_and_b32 s99, s34, 1
	s_mul_i32 s98, s99, 0x4800
	s_addk_i32 s98, 0x6800
	s_mulk_i32 s99, 0x6800
	s_add_i32 s99, s99, s44
	s_add_i32 s98, s98, s44
	s_lshl_b32 s94, s34, 18
	s_lshl_b32 s90, s34, 13
	s_lshl_b32 s91, s34, 7
	s_lshl_b32 s92, s34, s96
	s_cmp_ge_u32 s45, 2
	s_cselect_b32 s93, s98, s99
	s_add_i32 m0, s93, 0x6000
	v_add_u32_e32 v255, s92, v221
	global_load_lds_dwordx4 v255, s[50:51]
	s_add_i32 m0, s98, 0x7000
	v_add_u32_e32 v255, s91, v222
	global_load_lds_dwordx4 v255, s[54:55]
	s_add_i32 m0, s98, 0x8000
	v_add_u32_e32 v255, s91, v223
	global_load_lds_dwordx4 v255, s[54:55]
	s_add_i32 m0, s98, 0x9000
	v_add_u32_e32 v255, s91, v224
	global_load_lds_dwordx4 v255, s[54:55]
	s_add_i32 m0, s98, 0xa000
	v_add_u32_e32 v255, s91, v225
	global_load_lds_dwordx4 v255, s[54:55]
.Ldmq_end:
	s_add_i32 vcc_lo, s15, 31
	s_cmp_le_i32 vcc_lo, s86
	s_cbranch_scc1 .LBB0_1281
	v_add_u32_e32 v208, s15, v232
	v_cmp_lt_i32_e32 vcc, v208, v228
	v_add_u32_e32 v209, 2, v208
	s_nop 4
	v_cndmask_b32_e32 v65, v213, v65, vcc
	v_cmp_le_i32_e32 vcc, v208, v228
	s_nop 1
	v_cndmask_b32_e32 v64, v213, v64, vcc
	v_cmp_le_i32_e32 vcc, v209, v228
	v_add_u32_e32 v209, 3, v208
	s_nop 0
	v_cndmask_b32_e32 v66, v213, v66, vcc
	v_cmp_le_i32_e32 vcc, v209, v228
	v_add_u32_e32 v209, 8, v208
	s_nop 0
	v_cndmask_b32_e32 v67, v213, v67, vcc
	v_cmp_le_i32_e32 vcc, v209, v228
	v_add_u32_e32 v209, 9, v208
	s_nop 0
	v_cndmask_b32_e32 v68, v213, v68, vcc
	v_cmp_le_i32_e32 vcc, v209, v228
	v_add_u32_e32 v209, 10, v208
	s_nop 0
	v_cndmask_b32_e32 v69, v213, v69, vcc
	v_cmp_le_i32_e32 vcc, v209, v228
	v_add_u32_e32 v209, 11, v208
	s_nop 0
	v_cndmask_b32_e32 v70, v213, v70, vcc
	v_cmp_le_i32_e32 vcc, v209, v228
	v_add_u32_e32 v209, 16, v208
	s_nop 0
	v_cndmask_b32_e32 v71, v213, v71, vcc
	v_cmp_le_i32_e32 vcc, v209, v228
	v_add_u32_e32 v209, 17, v208
	s_nop 0
	v_cndmask_b32_e32 v72, v213, v72, vcc
	v_cmp_le_i32_e32 vcc, v209, v228
	v_add_u32_e32 v209, 18, v208
	s_nop 0
	v_cndmask_b32_e32 v73, v213, v73, vcc
	v_cmp_le_i32_e32 vcc, v209, v228
	v_add_u32_e32 v209, 19, v208
	s_nop 0
	v_cndmask_b32_e32 v74, v213, v74, vcc
	v_cmp_le_i32_e32 vcc, v209, v228
	v_add_u32_e32 v209, 24, v208
	s_nop 0
	v_cndmask_b32_e32 v75, v213, v75, vcc
	v_cmp_le_i32_e32 vcc, v209, v228
	v_add_u32_e32 v209, 25, v208
	s_nop 0
	v_cndmask_b32_e32 v76, v213, v76, vcc
	v_cmp_le_i32_e32 vcc, v209, v228
	v_add_u32_e32 v209, 26, v208
	s_nop 0
	v_cndmask_b32_e32 v77, v213, v77, vcc
	v_cmp_le_i32_e32 vcc, v209, v228
	v_add_u32_e32 v209, 27, v208
	s_nop 0
	v_cndmask_b32_e32 v78, v213, v78, vcc
	v_cmp_le_i32_e32 vcc, v209, v228
	s_nop 1
	v_cndmask_b32_e32 v79, v213, v79, vcc
.LBB0_1281:
	s_nop 7
	v_max_f32_e32 v209, v64, v65
	v_max3_f32 v209, v209, v66, v67
	v_max3_f32 v209, v209, v68, v69
	v_max3_f32 v209, v209, v70, v71
	v_max3_f32 v209, v209, v72, v73
	v_max3_f32 v209, v209, v74, v75
	v_max3_f32 v209, v209, v76, v77
	v_max3_f32 v209, v209, v78, v79
	v_mov_b32_e32 v210, v209
	s_nop 1
	v_permlane32_swap_b32_e32 v209, v210
	v_max_f32_e32 v209, v209, v210
	v_cmp_gt_f32_e32 vcc, v209, v252
	s_cbranch_vccz .LBB0_1283
	v_max_f32_e32 v209, v209, v209
	v_max_f32_e32 v210, v236, v236
	v_max_f32_e32 v209, v210, v209
	v_sub_f32_e32 v210, v236, v209
	v_exp_f32_e32 v210, v210
	v_mov_b32_e32 v236, v209
	v_add_f32_e32 v252, 0x41000000, v209
	v_pk_mul_f32 v[62:63], v[62:63], v[210:211] op_sel_hi:[1,0]
	v_pk_mul_f32 v[60:61], v[60:61], v[210:211] op_sel_hi:[1,0]
	v_pk_mul_f32 v[58:59], v[58:59], v[210:211] op_sel_hi:[1,0]
	v_pk_mul_f32 v[56:57], v[56:57], v[210:211] op_sel_hi:[1,0]
	v_pk_mul_f32 v[54:55], v[54:55], v[210:211] op_sel_hi:[1,0]
	v_pk_mul_f32 v[52:53], v[52:53], v[210:211] op_sel_hi:[1,0]
	v_pk_mul_f32 v[50:51], v[50:51], v[210:211] op_sel_hi:[1,0]
	v_pk_mul_f32 v[48:49], v[48:49], v[210:211] op_sel_hi:[1,0]
	v_pk_mul_f32 v[46:47], v[46:47], v[210:211] op_sel_hi:[1,0]
	v_pk_mul_f32 v[44:45], v[44:45], v[210:211] op_sel_hi:[1,0]
	v_pk_mul_f32 v[42:43], v[42:43], v[210:211] op_sel_hi:[1,0]
	v_pk_mul_f32 v[40:41], v[40:41], v[210:211] op_sel_hi:[1,0]
	v_pk_mul_f32 v[38:39], v[38:39], v[210:211] op_sel_hi:[1,0]
	v_pk_mul_f32 v[36:37], v[36:37], v[210:211] op_sel_hi:[1,0]
	v_pk_mul_f32 v[34:35], v[34:35], v[210:211] op_sel_hi:[1,0]
	v_pk_mul_f32 v[32:33], v[32:33], v[210:211] op_sel_hi:[1,0]
	v_pk_mul_f32 v[30:31], v[30:31], v[210:211] op_sel_hi:[1,0]
	v_pk_mul_f32 v[28:29], v[28:29], v[210:211] op_sel_hi:[1,0]
	v_pk_mul_f32 v[26:27], v[26:27], v[210:211] op_sel_hi:[1,0]
	v_pk_mul_f32 v[24:25], v[24:25], v[210:211] op_sel_hi:[1,0]
	v_pk_mul_f32 v[22:23], v[22:23], v[210:211] op_sel_hi:[1,0]
	v_pk_mul_f32 v[20:21], v[20:21], v[210:211] op_sel_hi:[1,0]
	v_pk_mul_f32 v[18:19], v[18:19], v[210:211] op_sel_hi:[1,0]
	v_pk_mul_f32 v[16:17], v[16:17], v[210:211] op_sel_hi:[1,0]
	v_pk_mul_f32 v[14:15], v[14:15], v[210:211] op_sel_hi:[1,0]
	v_pk_mul_f32 v[12:13], v[12:13], v[210:211] op_sel_hi:[1,0]
	v_pk_mul_f32 v[10:11], v[10:11], v[210:211] op_sel_hi:[1,0]
	v_pk_mul_f32 v[8:9], v[8:9], v[210:211] op_sel_hi:[1,0]
	v_pk_mul_f32 v[6:7], v[6:7], v[210:211] op_sel_hi:[1,0]
	v_pk_mul_f32 v[4:5], v[4:5], v[210:211] op_sel_hi:[1,0]
	v_pk_mul_f32 v[2:3], v[2:3], v[210:211] op_sel_hi:[1,0]
	v_pk_mul_f32 v[0:1], v[0:1], v[210:211] op_sel_hi:[1,0]
	v_mul_f32_e32 v235, v235, v210
.LBB0_1283:
	v_sub_f32_e32 v64, v64, v236
	v_exp_f32_e32 v209, v64
	v_sub_f32_e32 v64, v65, v236
	v_exp_f32_e32 v210, v64
	v_sub_f32_e32 v64, v66, v236
	v_exp_f32_e32 v211, v64
	v_sub_f32_e32 v64, v67, v236
	v_exp_f32_e32 v239, v64
	v_sub_f32_e32 v64, v68, v236
	v_exp_f32_e32 v240, v64
	v_sub_f32_e32 v64, v69, v236
	v_exp_f32_e32 v241, v64
	v_sub_f32_e32 v64, v70, v236
	v_exp_f32_e32 v242, v64
	v_sub_f32_e32 v64, v71, v236
	v_exp_f32_e32 v243, v64
	v_sub_f32_e32 v64, v72, v236
	v_exp_f32_e32 v244, v64
	v_sub_f32_e32 v64, v73, v236
	v_exp_f32_e32 v245, v64
	v_sub_f32_e32 v64, v74, v236
	v_exp_f32_e32 v246, v64
	v_sub_f32_e32 v64, v75, v236
	v_exp_f32_e32 v247, v64
	v_sub_f32_e32 v64, v76, v236
	v_exp_f32_e32 v248, v64
	v_sub_f32_e32 v64, v77, v236
	v_exp_f32_e32 v249, v64
	v_sub_f32_e32 v64, v78, v236
	v_exp_f32_e32 v250, v64
	v_sub_f32_e32 v64, v79, v236
	v_exp_f32_e32 v251, v64
	v_cvt_pk_bf16_f32 v64, v209, v210
	v_cvt_pk_bf16_f32 v65, v211, v239
	v_cvt_pk_bf16_f32 v66, v240, v241
	v_cvt_pk_bf16_f32 v67, v242, v243
	v_cvt_pk_bf16_f32 v68, v244, v245
	v_cvt_pk_bf16_f32 v69, v246, v247
	v_cvt_pk_bf16_f32 v70, v248, v249
	v_cvt_pk_bf16_f32 v71, v250, v251
	s_barrier
	s_setprio 1
	s_waitcnt lgkmcnt(0)
	v_mfma_f32_32x32x16_bf16 v[48:63], v[180:183], v[64:67], v[48:63]
	v_mfma_f32_32x32x16_bf16 v[32:47], v[196:199], v[64:67], v[32:47]
	v_mfma_f32_32x32x16_bf16 v[16:31], v[188:191], v[64:67], v[16:31]
	v_mfma_f32_32x32x16_bf16 v[0:15], v[200:203], v[64:67], v[0:15]
	v_mfma_f32_32x32x16_bf16 v[48:63], v[176:179], v[68:71], v[48:63]
	v_mfma_f32_32x32x16_bf16 v[32:47], v[204:207], v[68:71], v[32:47]
	v_mfma_f32_32x32x16_bf16 v[16:31], v[192:195], v[68:71], v[16:31]
	v_mfma_f32_32x32x16_bf16 v[0:15], v[184:187], v[68:71], v[0:15]
	s_setprio 0
	s_setprio 1
	v_mfma_f32_32x32x16_bf16 v[64:79], v[168:171], v[80:83], 0
	ds_read_b128 v[180:183], v237 offset:53312
	v_mfma_f32_32x32x16_bf16 v[64:79], v[160:163], v[84:87], v[64:79]
	ds_read_b128 v[176:179], v237 offset:53344
	v_mfma_f32_32x32x16_bf16 v[64:79], v[164:167], v[88:91], v[64:79]
	ds_read_b128 v[184:187], v237 offset:57920
	v_mfma_f32_32x32x16_bf16 v[64:79], v[152:155], v[92:95], v[64:79]
	ds_read_b128 v[192:195], v237 offset:62528
	v_mfma_f32_32x32x16_bf16 v[64:79], v[156:159], v[96:99], v[64:79]
	ds_read_b128 v[196:199], v238 offset:13888
	v_mfma_f32_32x32x16_bf16 v[64:79], v[128:131], v[100:103], v[64:79]
	ds_read_b128 v[188:191], v238 offset:13920
	v_mfma_f32_32x32x16_bf16 v[64:79], v[132:135], v[104:107], v[64:79]
	ds_read_b128 v[200:203], v237 offset:57952
	v_mfma_f32_32x32x16_bf16 v[64:79], v[136:139], v[108:111], v[64:79]
	ds_read_b128 v[204:207], v237 offset:62560
	v_mfma_f32_32x32x16_bf16 v[64:79], v[140:143], v[112:115], v[64:79]
	v_mfma_f32_32x32x16_bf16 v[64:79], v[144:147], v[116:119], v[64:79]
	v_mfma_f32_32x32x16_bf16 v[64:79], v[148:151], v[120:123], v[64:79]
	v_mfma_f32_32x32x16_bf16 v[64:79], v[172:175], v[124:127], v[64:79]
	s_setprio 0
	s_waitcnt vmcnt(0) lgkmcnt(0)
	s_barrier
	s_add_i32 vcc_lo, s15, 63
	s_cmp_le_i32 vcc_lo, s86
	s_cbranch_scc1 .LBB0_1285
	v_add_u32_e32 v208, s15, v232
	v_add_u32_e32 v237, 32, v208
	v_cmp_lt_i32_e32 vcc, v237, v228
	s_nop 5
	v_cndmask_b32_e32 v65, v213, v65, vcc
	v_cmp_le_i32_e32 vcc, v237, v228
	v_add_u32_e32 v237, 34, v208
	s_nop 0
	v_cndmask_b32_e32 v64, v213, v64, vcc
	v_cmp_le_i32_e32 vcc, v237, v228
	v_add_u32_e32 v237, 35, v208
	s_nop 0
	v_cndmask_b32_e32 v66, v213, v66, vcc
	v_cmp_le_i32_e32 vcc, v237, v228
	v_add_u32_e32 v237, 40, v208
	s_nop 0
	v_cndmask_b32_e32 v67, v213, v67, vcc
	v_cmp_le_i32_e32 vcc, v237, v228
	v_add_u32_e32 v237, 41, v208
	s_nop 0
	v_cndmask_b32_e32 v68, v213, v68, vcc
	v_cmp_le_i32_e32 vcc, v237, v228
	v_add_u32_e32 v237, 42, v208
	s_nop 0
	v_cndmask_b32_e32 v69, v213, v69, vcc
	v_cmp_le_i32_e32 vcc, v237, v228
	v_add_u32_e32 v237, 43, v208
	s_nop 0
	v_cndmask_b32_e32 v70, v213, v70, vcc
	v_cmp_le_i32_e32 vcc, v237, v228
	v_add_u32_e32 v237, 48, v208
	s_nop 0
	v_cndmask_b32_e32 v71, v213, v71, vcc
	v_cmp_le_i32_e32 vcc, v237, v228
	v_add_u32_e32 v237, 49, v208
	s_nop 0
	v_cndmask_b32_e32 v72, v213, v72, vcc
	v_cmp_le_i32_e32 vcc, v237, v228
	v_add_u32_e32 v237, 50, v208
	s_nop 0
	v_cndmask_b32_e32 v73, v213, v73, vcc
	v_cmp_le_i32_e32 vcc, v237, v228
	v_add_u32_e32 v237, 51, v208
	s_nop 0
	v_cndmask_b32_e32 v74, v213, v74, vcc
	v_cmp_le_i32_e32 vcc, v237, v228
	v_add_u32_e32 v237, 56, v208
	s_nop 0
	v_cndmask_b32_e32 v75, v213, v75, vcc
	v_cmp_le_i32_e32 vcc, v237, v228
	v_add_u32_e32 v237, 57, v208
	s_nop 0
	v_cndmask_b32_e32 v76, v213, v76, vcc
	v_cmp_le_i32_e32 vcc, v237, v228
	v_add_u32_e32 v237, 58, v208
	v_add_u32_e32 v208, 59, v208
	v_cndmask_b32_e32 v77, v213, v77, vcc
	v_cmp_le_i32_e32 vcc, v237, v228
	s_nop 1
	v_cndmask_b32_e32 v78, v213, v78, vcc
	v_cmp_le_i32_e32 vcc, v208, v228
	s_nop 1
	v_cndmask_b32_e32 v79, v213, v79, vcc
.LBB0_1285:
	v_add_f32_e32 v208, v209, v210
	v_add_f32_e32 v208, v211, v208
	v_add_f32_e32 v208, v239, v208
	s_nop 4
	v_max_f32_e32 v209, v64, v65
	v_add_f32_e32 v208, v240, v208
	v_max3_f32 v209, v209, v66, v67
	v_add_f32_e32 v208, v241, v208
	v_max3_f32 v209, v209, v68, v69
	v_add_f32_e32 v208, v242, v208
	v_max3_f32 v209, v209, v70, v71
	v_add_f32_e32 v208, v243, v208
	v_max3_f32 v209, v209, v72, v73
	v_add_f32_e32 v208, v244, v208
	v_max3_f32 v209, v209, v74, v75
	v_add_f32_e32 v208, v245, v208
	v_max3_f32 v209, v209, v76, v77
	v_add_f32_e32 v208, v246, v208
	v_max3_f32 v209, v209, v78, v79
	v_add_f32_e32 v208, v247, v208
	v_mov_b32_e32 v210, v209
	v_add_f32_e32 v208, v248, v208
	v_add_f32_e32 v208, v249, v208
	v_permlane32_swap_b32_e32 v209, v210
	v_add_f32_e32 v208, v250, v208
	v_max_f32_e32 v209, v209, v210
	v_add_f32_e32 v208, v251, v208
	v_add_f32_e32 v208, v235, v208
	v_cmp_gt_f32_e32 vcc, v209, v252
	s_cbranch_vccz .LBB0_1287
	v_max_f32_e32 v209, v209, v209
	v_max_f32_e32 v210, v236, v236
	v_max_f32_e32 v209, v210, v209
	v_sub_f32_e32 v210, v236, v209
	v_exp_f32_e32 v210, v210
	v_mov_b32_e32 v236, v209
	v_add_f32_e32 v252, 0x41000000, v209
	v_pk_mul_f32 v[62:63], v[62:63], v[210:211] op_sel_hi:[1,0]
	v_pk_mul_f32 v[60:61], v[60:61], v[210:211] op_sel_hi:[1,0]
	v_pk_mul_f32 v[58:59], v[58:59], v[210:211] op_sel_hi:[1,0]
	v_pk_mul_f32 v[56:57], v[56:57], v[210:211] op_sel_hi:[1,0]
	v_pk_mul_f32 v[54:55], v[54:55], v[210:211] op_sel_hi:[1,0]
	v_pk_mul_f32 v[52:53], v[52:53], v[210:211] op_sel_hi:[1,0]
	v_pk_mul_f32 v[50:51], v[50:51], v[210:211] op_sel_hi:[1,0]
	v_pk_mul_f32 v[48:49], v[48:49], v[210:211] op_sel_hi:[1,0]
	v_pk_mul_f32 v[46:47], v[46:47], v[210:211] op_sel_hi:[1,0]
	v_pk_mul_f32 v[44:45], v[44:45], v[210:211] op_sel_hi:[1,0]
	v_pk_mul_f32 v[42:43], v[42:43], v[210:211] op_sel_hi:[1,0]
	v_pk_mul_f32 v[40:41], v[40:41], v[210:211] op_sel_hi:[1,0]
	v_pk_mul_f32 v[38:39], v[38:39], v[210:211] op_sel_hi:[1,0]
	v_pk_mul_f32 v[36:37], v[36:37], v[210:211] op_sel_hi:[1,0]
	v_pk_mul_f32 v[34:35], v[34:35], v[210:211] op_sel_hi:[1,0]
	v_pk_mul_f32 v[32:33], v[32:33], v[210:211] op_sel_hi:[1,0]
	v_pk_mul_f32 v[30:31], v[30:31], v[210:211] op_sel_hi:[1,0]
	v_pk_mul_f32 v[28:29], v[28:29], v[210:211] op_sel_hi:[1,0]
	v_pk_mul_f32 v[26:27], v[26:27], v[210:211] op_sel_hi:[1,0]
	v_pk_mul_f32 v[24:25], v[24:25], v[210:211] op_sel_hi:[1,0]
	v_pk_mul_f32 v[22:23], v[22:23], v[210:211] op_sel_hi:[1,0]
	v_pk_mul_f32 v[20:21], v[20:21], v[210:211] op_sel_hi:[1,0]
	v_pk_mul_f32 v[18:19], v[18:19], v[210:211] op_sel_hi:[1,0]
	v_pk_mul_f32 v[16:17], v[16:17], v[210:211] op_sel_hi:[1,0]
	v_pk_mul_f32 v[14:15], v[14:15], v[210:211] op_sel_hi:[1,0]
	v_pk_mul_f32 v[12:13], v[12:13], v[210:211] op_sel_hi:[1,0]
	v_pk_mul_f32 v[10:11], v[10:11], v[210:211] op_sel_hi:[1,0]
	v_pk_mul_f32 v[8:9], v[8:9], v[210:211] op_sel_hi:[1,0]
	v_pk_mul_f32 v[6:7], v[6:7], v[210:211] op_sel_hi:[1,0]
	v_pk_mul_f32 v[4:5], v[4:5], v[210:211] op_sel_hi:[1,0]
	v_pk_mul_f32 v[2:3], v[2:3], v[210:211] op_sel_hi:[1,0]
	v_pk_mul_f32 v[0:1], v[0:1], v[210:211] op_sel_hi:[1,0]
	v_mul_f32_e32 v208, v208, v210

.LBB0_1288:
	s_barrier
	s_and_b64 vcc, exec, s[68:69]
	s_cbranch_vccnz .Ldmr_end
	s_cmp_ge_u32 s85, 4
	s_cbranch_scc1 .Lxdr_y
	s_and_b32 s99, s34, 1
	s_mul_i32 s98, s99, 0x4800
	s_addk_i32 s98, 0x6800
	s_mulk_i32 s99, 0x6800
	s_add_i32 s99, s99, s44
	s_add_i32 s98, s98, s44
	s_lshl_b32 s94, s34, 18
	s_lshl_b32 s90, s34, 13
	s_lshl_b32 s91, s34, 7
	s_add_i32 m0, s99, 0x0
	v_add_u32_e32 v255, s94, v221
	global_load_lds_dwordx4 v255, s[8:9]
	s_add_i32 m0, s99, 0x1000
	v_add_u32_e32 v255, s94, v222
	global_load_lds_dwordx4 v255, s[8:9]
	s_add_i32 m0, s99, 0x2000
	v_add_u32_e32 v255, s94, v223
	global_load_lds_dwordx4 v255, s[8:9]
	s_add_i32 m0, s99, 0x3000
	v_add_u32_e32 v255, s94, v224
	global_load_lds_dwordx4 v255, s[8:9]
	s_lshl_b32 s92, s34, s95
	s_add_i32 m0, s99, 0x4000
	v_add_u32_e32 v255, s92, v225
	global_load_lds_dwordx4 v255, s[46:47]
	s_add_i32 m0, s99, 0x5000
	v_add_u32_e32 v255, s90, v226
	global_load_lds_dwordx4 v255, s[52:53]
	s_branch .Ldmr_end

.LBB0_1289:
	s_cmp_ge_i32 s35, s89
	s_waitcnt vmcnt(0) lgkmcnt(0)
	s_cselect_b64 vcc, -1, 0
	s_or_b64 s[68:69], vcc, s[68:69]
	s_and_b64 vcc, exec, s[68:69]
	s_waitcnt vmcnt(0) lgkmcnt(0)
	s_barrier
	s_andn2_b64 s[100:101], s[70:71], s[68:69]
	s_and_b64 vcc, exec, s[100:101]
	s_cbranch_vccz .Lpp_slow
	s_bitcmp1_b32 s34, 0
	s_cselect_b32 s35, 0x6800, 0
	v_add_u32_e32 v72, s35, v230
	v_add_u32_e32 v73, s35, v231
	s_setprio 1
	v_mfma_f32_32x32x16_bf16 v[48:63], v[180:183], v[64:67], v[48:63]
	ds_read_b128 v[168:171], v72
	ds_read_b128 v[160:163], v72 offset:32
	v_mfma_f32_32x32x16_bf16 v[32:47], v[184:187], v[64:67], v[32:47]
	ds_read_b128 v[164:167], v72 offset:64
	ds_read_b128 v[152:155], v72 offset:96
	v_mfma_f32_32x32x16_bf16 v[16:31], v[192:195], v[64:67], v[16:31]
	ds_read_b128 v[156:159], v72 offset:128
	ds_read_b128 v[128:131], v72 offset:160
	v_mfma_f32_32x32x16_bf16 v[0:15], v[196:199], v[64:67], v[0:15]
	ds_read_b128 v[132:135], v72 offset:192
	ds_read_b128 v[136:139], v72 offset:224
	v_mfma_f32_32x32x16_bf16 v[48:63], v[176:179], v[68:71], v[48:63]
	ds_read_b128 v[140:143], v73 offset:17408
	ds_read_b128 v[144:147], v73 offset:17440
	v_mfma_f32_32x32x16_bf16 v[32:47], v[200:203], v[68:71], v[32:47]
	ds_read_b128 v[148:151], v73 offset:17472
	ds_read_b128 v[172:175], v73 offset:17504
	v_mfma_f32_32x32x16_bf16 v[16:31], v[204:207], v[68:71], v[16:31]
	v_mfma_f32_32x32x16_bf16 v[0:15], v[188:191], v[68:71], v[0:15]
	s_setprio 0
	s_branch .LBB0_1293
.Lpp_slow:
	s_and_b64 vcc, exec, s[68:69]
	s_cbranch_vccnz .LBB0_1291
	s_bitcmp1_b32 s34, 0
	s_cselect_b32 s35, 0x6800, 0
	v_add_u32_e32 v72, s35, v230
	ds_read_b128 v[168:171], v72
	ds_read_b128 v[160:163], v72 offset:32
	ds_read_b128 v[164:167], v72 offset:64
	ds_read_b128 v[152:155], v72 offset:96
	ds_read_b128 v[156:159], v72 offset:128
	ds_read_b128 v[128:131], v72 offset:160
	ds_read_b128 v[132:135], v72 offset:192
	ds_read_b128 v[136:139], v72 offset:224
	v_add_u32_e32 v72, s35, v231
	ds_read_b128 v[140:143], v72 offset:17408
	ds_read_b128 v[144:147], v72 offset:17440
	ds_read_b128 v[148:151], v72 offset:17472
	ds_read_b128 v[172:175], v72 offset:17504

.LBB0_1296:
	v_lshlrev_b32_e32 v212, 2, v216
	v_and_b32_e32 v217, 63, v216
	v_lshrrev_b32_e32 v218, 6, v216
	s_waitcnt vmcnt(0)
	s_barrier
	s_mov_b64 s[4:5], exec
	v_readlane_b32 s0, v254, 7
	v_readlane_b32 s1, v254, 8
	s_and_b64 s[0:1], s[4:5], s[0:1]
	s_mov_b64 exec, s[0:1]
	s_cbranch_execz .LBB0_1348
	s_add_i32 s0, 0, 0x23ff0
	v_mov_b32_e32 v0, s0
	s_waitcnt vmcnt(0) expcnt(0) lgkmcnt(0)
	ds_read_b32 v2, v0
	s_add_i32 s0, 0, 0x23ff4
	v_mov_b32_e32 v0, s0
	ds_read_b32 v0, v0
	s_waitcnt lgkmcnt(1)
	v_cmp_ne_u32_e32 vcc, 0, v2
	s_cbranch_vccnz .LBB0_1312
	v_readlane_b32 s6, v254, 0
	v_readlane_b32 s7, v254, 1
	v_readlane_b32 s0, v254, 2
	s_mul_i32 s0, s7, s0
	s_mul_i32 s0, s0, s6
	v_readlane_b32 s6, v254, 14
	v_readlane_b32 s7, v254, 15
	s_add_u32 s8, s6, 0x40200
	s_addc_u32 s9, s7, 0
	s_add_u32 s10, s6, 0x40400
	s_addc_u32 s11, s7, 0
	s_add_u32 s12, s6, 0x40500
	s_addc_u32 s13, s7, 0
	s_add_u32 s16, s6, 0x40600
	s_addc_u32 s17, s7, 0
	s_add_u32 s18, s6, 0x40700
	s_addc_u32 s19, s7, 0
	s_add_u32 s20, s6, 0x40800
	s_addc_u32 s21, s7, 0
	s_add_u32 s22, s6, 0x40900
	s_addc_u32 s23, s7, 0
	s_add_u32 s24, s6, 0x40a00
	s_addc_u32 s25, s7, 0
	s_add_u32 s30, s6, 0x40b00
	s_addc_u32 s31, s7, 0
	s_add_u32 s42, s6, 0x40c00
	s_addc_u32 s43, s7, 0
	s_add_u32 s44, s6, 0x40d00
	s_addc_u32 s45, s7, 0
	s_add_u32 s46, s6, 0x40e00
	s_addc_u32 s47, s7, 0
	s_add_u32 s48, s6, 0x40f00
	s_addc_u32 s49, s7, 0
	s_add_u32 s50, s6, 0x41000
	s_addc_u32 s51, s7, 0
	s_add_u32 s52, s6, 0x41100
	s_addc_u32 s53, s7, 0
	s_add_u32 s54, s6, 0x41200
	s_addc_u32 s55, s7, 0
	s_add_u32 s56, s6, 0x41300
	s_addc_u32 s57, s7, 0
	s_mov_b32 s1, 1
	v_mov_b32_e32 v16, 0
	s_branch .LBB0_1300

	.amdhsa_kernel _Z8mega_fwd6Params
		.amdhsa_group_segment_fixed_size 0
		.amdhsa_private_segment_fixed_size 0
		.amdhsa_kernarg_size 728
		.amdhsa_user_sgpr_count 2
		.amdhsa_user_sgpr_dispatch_ptr 0
		.amdhsa_user_sgpr_queue_ptr 0
		.amdhsa_user_sgpr_kernarg_segment_ptr 1
		.amdhsa_user_sgpr_dispatch_id 0
		.amdhsa_user_sgpr_kernarg_preload_length 0
		.amdhsa_user_sgpr_kernarg_preload_offset 0
		.amdhsa_user_sgpr_private_segment_size 0
		.amdhsa_uses_dynamic_stack 0
		.amdhsa_enable_private_segment 0
		.amdhsa_system_sgpr_workgroup_id_x 1
		.amdhsa_system_sgpr_workgroup_id_y 0
		.amdhsa_system_sgpr_workgroup_id_z 0
		.amdhsa_system_sgpr_workgroup_info 0
		.amdhsa_system_vgpr_workitem_id 2
		.amdhsa_next_free_vgpr 256
		.amdhsa_next_free_sgpr 102
		.amdhsa_accum_offset 256
		.amdhsa_reserve_vcc 1
		.amdhsa_float_round_mode_32 0
		.amdhsa_float_round_mode_16_64 0
		.amdhsa_float_denorm_mode_32 3
		.amdhsa_float_denorm_mode_16_64 3
		.amdhsa_dx10_clamp 1
		.amdhsa_ieee_mode 1
		.amdhsa_fp16_overflow 0
		.amdhsa_tg_split 0
		.amdhsa_exception_fp_ieee_invalid_op 0
		.amdhsa_exception_fp_denorm_src 0
		.amdhsa_exception_fp_ieee_div_zero 0
		.amdhsa_exception_fp_ieee_overflow 0
		.amdhsa_exception_fp_ieee_underflow 0
		.amdhsa_exception_fp_ieee_inexact 0
		.amdhsa_exception_int_div_zero 0
	.end_amdhsa_kernel

amdhsa.kernels:
  - .agpr_count:     0
    .args:
      - .offset:         0
        .size:           472
        .value_kind:     by_value
      - .offset:         472
        .size:           4
        .value_kind:     hidden_block_count_x
      - .offset:         476
        .size:           4
        .value_kind:     hidden_block_count_y
      - .offset:         480
        .size:           4
        .value_kind:     hidden_block_count_z
      - .offset:         484
        .size:           2
        .value_kind:     hidden_group_size_x
      - .offset:         486
        .size:           2
        .value_kind:     hidden_group_size_y
      - .offset:         488
        .size:           2
        .value_kind:     hidden_group_size_z
      - .offset:         490
        .size:           2
        .value_kind:     hidden_remainder_x
      - .offset:         492
        .size:           2
        .value_kind:     hidden_remainder_y
      - .offset:         494
        .size:           2
        .value_kind:     hidden_remainder_z
      - .offset:         512
        .size:           8
        .value_kind:     hidden_global_offset_x
      - .offset:         520
        .size:           8
        .value_kind:     hidden_global_offset_y
      - .offset:         528
        .size:           8
        .value_kind:     hidden_global_offset_z
      - .offset:         536
        .size:           2
        .value_kind:     hidden_grid_dims
      - .offset:         560
        .size:           8
        .value_kind:     hidden_multigrid_sync_arg
      - .offset:         592
        .size:           4
        .value_kind:     hidden_dynamic_lds_size
    .group_segment_fixed_size: 0
    .kernarg_segment_align: 8
    .kernarg_segment_size: 728
    .language:       OpenCL C
    .language_version:
      - 2
      - 0
    .max_flat_workgroup_size: 512
    .name:           _Z8mega_fwd6Params
    .private_segment_fixed_size: 0
    .sgpr_count:     108
    .sgpr_spill_count: 22
    .symbol:         _Z8mega_fwd6Params.kd
    .uniform_work_group_size: 1
    .uses_dynamic_stack: false
    .vgpr_count:     256
    .vgpr_spill_count: 0
    .wavefront_size: 64
